# RMSNorm phases rewritten by hand: all 8 tokens of a wave in flight, swizzle reductions
# speedup vs baseline: 1.2365x; 1.0081x over previous
.LBB0_69:
	s_andn2_b64 vcc, exec, s[0:1]
	s_cbranch_vccnz .LBB0_74
	v_and_b32_e32 v185, 63, v163
	v_lshlrev_b32_e32 v182, 4, v185
	v_lshlrev_b32_e32 v183, 3, v185
	v_xor_b32_e32 v184, 32, v185
	v_lshlrev_b32_e32 v184, 2, v184
	v_lshrrev_b32_e32 v186, 6, v163
	v_readlane_b32 s2, v236, 47
	v_readlane_b32 s3, v236, 48
	global_load_dword v185, v[164:165], off
	s_nop 3
	global_load_dwordx4 v[130:133], v182, s[2:3] offset:0
	global_load_dwordx4 v[134:137], v182, s[2:3] offset:1024
	global_load_dwordx4 v[138:141], v182, s[2:3] offset:2048
	global_load_dwordx4 v[142:145], v182, s[2:3] offset:3072
	v_readlane_b32 s2, v237, 0
	v_readfirstlane_b32 s3, v186
	s_lshl_b32 s2, s2, 2
	s_add_i32 s2, s2, s3
	s_waitcnt vmcnt(4)
	v_readfirstlane_b32 s3, v185
	s_lshl_b32 s3, s3, 2
.Lr8_outer:
	s_mov_b32 s0, s44
	s_mov_b32 s1, s45
	s_lshl_b32 s4, s2, 12
	s_add_u32 s0, s0, s4
	s_addc_u32 s1, s1, 0
	s_mov_b32 s6, s2
	s_cmpk_ge_u32 s6, 0x4000
	s_cbranch_scc1 .Lr8_ld0
	global_load_dwordx4 v[2:5], v182, s[0:1] offset:0
	global_load_dwordx4 v[6:9], v182, s[0:1] offset:1024
	global_load_dwordx4 v[10:13], v182, s[0:1] offset:2048
	global_load_dwordx4 v[14:17], v182, s[0:1] offset:3072
.Lr8_ld0:
	s_lshl_b32 s4, s3, 12
	s_add_u32 s0, s0, s4
	s_addc_u32 s1, s1, 0
	s_add_i32 s6, s6, s3
	s_cmpk_ge_u32 s6, 0x4000
	s_cbranch_scc1 .Lr8_ld1
	global_load_dwordx4 v[18:21], v182, s[0:1] offset:0
	global_load_dwordx4 v[22:25], v182, s[0:1] offset:1024
	global_load_dwordx4 v[26:29], v182, s[0:1] offset:2048
	global_load_dwordx4 v[30:33], v182, s[0:1] offset:3072
.Lr8_ld1:
	s_lshl_b32 s4, s3, 12
	s_add_u32 s0, s0, s4
	s_addc_u32 s1, s1, 0
	s_add_i32 s6, s6, s3
	s_cmpk_ge_u32 s6, 0x4000
	s_cbranch_scc1 .Lr8_ld2
	global_load_dwordx4 v[34:37], v182, s[0:1] offset:0
	global_load_dwordx4 v[38:41], v182, s[0:1] offset:1024
	global_load_dwordx4 v[42:45], v182, s[0:1] offset:2048
	global_load_dwordx4 v[46:49], v182, s[0:1] offset:3072
.Lr8_ld2:
	s_lshl_b32 s4, s3, 12
	s_add_u32 s0, s0, s4
	s_addc_u32 s1, s1, 0
	s_add_i32 s6, s6, s3
	s_cmpk_ge_u32 s6, 0x4000
	s_cbranch_scc1 .Lr8_ld3
	global_load_dwordx4 v[50:53], v182, s[0:1] offset:0
	global_load_dwordx4 v[54:57], v182, s[0:1] offset:1024
	global_load_dwordx4 v[58:61], v182, s[0:1] offset:2048
	global_load_dwordx4 v[62:65], v182, s[0:1] offset:3072
.Lr8_ld3:
	s_lshl_b32 s4, s3, 12
	s_add_u32 s0, s0, s4
	s_addc_u32 s1, s1, 0
	s_add_i32 s6, s6, s3
	s_cmpk_ge_u32 s6, 0x4000
	s_cbranch_scc1 .Lr8_ld4
	global_load_dwordx4 v[66:69], v182, s[0:1] offset:0
	global_load_dwordx4 v[70:73], v182, s[0:1] offset:1024
	global_load_dwordx4 v[74:77], v182, s[0:1] offset:2048
	global_load_dwordx4 v[78:81], v182, s[0:1] offset:3072
.Lr8_ld4:
	s_lshl_b32 s4, s3, 12
	s_add_u32 s0, s0, s4
	s_addc_u32 s1, s1, 0
	s_add_i32 s6, s6, s3
	s_cmpk_ge_u32 s6, 0x4000
	s_cbranch_scc1 .Lr8_ld5
	global_load_dwordx4 v[82:85], v182, s[0:1] offset:0
	global_load_dwordx4 v[86:89], v182, s[0:1] offset:1024
	global_load_dwordx4 v[90:93], v182, s[0:1] offset:2048
	global_load_dwordx4 v[94:97], v182, s[0:1] offset:3072
.Lr8_ld5:
	s_lshl_b32 s4, s3, 12
	s_add_u32 s0, s0, s4
	s_addc_u32 s1, s1, 0
	s_add_i32 s6, s6, s3
	s_cmpk_ge_u32 s6, 0x4000
	s_cbranch_scc1 .Lr8_ld6
	global_load_dwordx4 v[98:101], v182, s[0:1] offset:0
	global_load_dwordx4 v[102:105], v182, s[0:1] offset:1024
	global_load_dwordx4 v[106:109], v182, s[0:1] offset:2048
	global_load_dwordx4 v[110:113], v182, s[0:1] offset:3072
.Lr8_ld6:
	s_lshl_b32 s4, s3, 12
	s_add_u32 s0, s0, s4
	s_addc_u32 s1, s1, 0
	s_add_i32 s6, s6, s3
	s_cmpk_ge_u32 s6, 0x4000
	s_cbranch_scc1 .Lr8_ld7
	global_load_dwordx4 v[114:117], v182, s[0:1] offset:0
	global_load_dwordx4 v[118:121], v182, s[0:1] offset:1024
	global_load_dwordx4 v[122:125], v182, s[0:1] offset:2048
	global_load_dwordx4 v[126:129], v182, s[0:1] offset:3072
.Lr8_ld7:
	s_waitcnt vmcnt(0)
	v_mul_f32_e32 v146, v2, v2
	v_fmac_f32_e32 v146, v3, v3
	v_fmac_f32_e32 v146, v4, v4
	v_fmac_f32_e32 v146, v5, v5
	v_fmac_f32_e32 v146, v6, v6
	v_fmac_f32_e32 v146, v7, v7
	v_fmac_f32_e32 v146, v8, v8
	v_fmac_f32_e32 v146, v9, v9
	v_fmac_f32_e32 v146, v10, v10
	v_fmac_f32_e32 v146, v11, v11
	v_fmac_f32_e32 v146, v12, v12
	v_fmac_f32_e32 v146, v13, v13
	v_fmac_f32_e32 v146, v14, v14
	v_fmac_f32_e32 v146, v15, v15
	v_fmac_f32_e32 v146, v16, v16
	v_fmac_f32_e32 v146, v17, v17
	v_mul_f32_e32 v147, v18, v18
	v_fmac_f32_e32 v147, v19, v19
	v_fmac_f32_e32 v147, v20, v20
	v_fmac_f32_e32 v147, v21, v21
	v_fmac_f32_e32 v147, v22, v22
	v_fmac_f32_e32 v147, v23, v23
	v_fmac_f32_e32 v147, v24, v24
	v_fmac_f32_e32 v147, v25, v25
	v_fmac_f32_e32 v147, v26, v26
	v_fmac_f32_e32 v147, v27, v27
	v_fmac_f32_e32 v147, v28, v28
	v_fmac_f32_e32 v147, v29, v29
	v_fmac_f32_e32 v147, v30, v30
	v_fmac_f32_e32 v147, v31, v31
	v_fmac_f32_e32 v147, v32, v32
	v_fmac_f32_e32 v147, v33, v33
	v_mul_f32_e32 v148, v34, v34
	v_fmac_f32_e32 v148, v35, v35
	v_fmac_f32_e32 v148, v36, v36
	v_fmac_f32_e32 v148, v37, v37
	v_fmac_f32_e32 v148, v38, v38
	v_fmac_f32_e32 v148, v39, v39
	v_fmac_f32_e32 v148, v40, v40
	v_fmac_f32_e32 v148, v41, v41
	v_fmac_f32_e32 v148, v42, v42
	v_fmac_f32_e32 v148, v43, v43
	v_fmac_f32_e32 v148, v44, v44
	v_fmac_f32_e32 v148, v45, v45
	v_fmac_f32_e32 v148, v46, v46
	v_fmac_f32_e32 v148, v47, v47
	v_fmac_f32_e32 v148, v48, v48
	v_fmac_f32_e32 v148, v49, v49
	v_mul_f32_e32 v149, v50, v50
	v_fmac_f32_e32 v149, v51, v51
	v_fmac_f32_e32 v149, v52, v52
	v_fmac_f32_e32 v149, v53, v53
	v_fmac_f32_e32 v149, v54, v54
	v_fmac_f32_e32 v149, v55, v55
	v_fmac_f32_e32 v149, v56, v56
	v_fmac_f32_e32 v149, v57, v57
	v_fmac_f32_e32 v149, v58, v58
	v_fmac_f32_e32 v149, v59, v59
	v_fmac_f32_e32 v149, v60, v60
	v_fmac_f32_e32 v149, v61, v61
	v_fmac_f32_e32 v149, v62, v62
	v_fmac_f32_e32 v149, v63, v63
	v_fmac_f32_e32 v149, v64, v64
	v_fmac_f32_e32 v149, v65, v65
	v_mul_f32_e32 v150, v66, v66
	v_fmac_f32_e32 v150, v67, v67
	v_fmac_f32_e32 v150, v68, v68
	v_fmac_f32_e32 v150, v69, v69
	v_fmac_f32_e32 v150, v70, v70
	v_fmac_f32_e32 v150, v71, v71
	v_fmac_f32_e32 v150, v72, v72
	v_fmac_f32_e32 v150, v73, v73
	v_fmac_f32_e32 v150, v74, v74
	v_fmac_f32_e32 v150, v75, v75
	v_fmac_f32_e32 v150, v76, v76
	v_fmac_f32_e32 v150, v77, v77
	v_fmac_f32_e32 v150, v78, v78
	v_fmac_f32_e32 v150, v79, v79
	v_fmac_f32_e32 v150, v80, v80
	v_fmac_f32_e32 v150, v81, v81
	v_mul_f32_e32 v151, v82, v82
	v_fmac_f32_e32 v151, v83, v83
	v_fmac_f32_e32 v151, v84, v84
	v_fmac_f32_e32 v151, v85, v85
	v_fmac_f32_e32 v151, v86, v86
	v_fmac_f32_e32 v151, v87, v87
	v_fmac_f32_e32 v151, v88, v88
	v_fmac_f32_e32 v151, v89, v89
	v_fmac_f32_e32 v151, v90, v90
	v_fmac_f32_e32 v151, v91, v91
	v_fmac_f32_e32 v151, v92, v92
	v_fmac_f32_e32 v151, v93, v93
	v_fmac_f32_e32 v151, v94, v94
	v_fmac_f32_e32 v151, v95, v95
	v_fmac_f32_e32 v151, v96, v96
	v_fmac_f32_e32 v151, v97, v97
	v_mul_f32_e32 v152, v98, v98
	v_fmac_f32_e32 v152, v99, v99
	v_fmac_f32_e32 v152, v100, v100
	v_fmac_f32_e32 v152, v101, v101
	v_fmac_f32_e32 v152, v102, v102
	v_fmac_f32_e32 v152, v103, v103
	v_fmac_f32_e32 v152, v104, v104
	v_fmac_f32_e32 v152, v105, v105
	v_fmac_f32_e32 v152, v106, v106
	v_fmac_f32_e32 v152, v107, v107
	v_fmac_f32_e32 v152, v108, v108
	v_fmac_f32_e32 v152, v109, v109
	v_fmac_f32_e32 v152, v110, v110
	v_fmac_f32_e32 v152, v111, v111
	v_fmac_f32_e32 v152, v112, v112
	v_fmac_f32_e32 v152, v113, v113
	v_mul_f32_e32 v153, v114, v114
	v_fmac_f32_e32 v153, v115, v115
	v_fmac_f32_e32 v153, v116, v116
	v_fmac_f32_e32 v153, v117, v117
	v_fmac_f32_e32 v153, v118, v118
	v_fmac_f32_e32 v153, v119, v119
	v_fmac_f32_e32 v153, v120, v120
	v_fmac_f32_e32 v153, v121, v121
	v_fmac_f32_e32 v153, v122, v122
	v_fmac_f32_e32 v153, v123, v123
	v_fmac_f32_e32 v153, v124, v124
	v_fmac_f32_e32 v153, v125, v125
	v_fmac_f32_e32 v153, v126, v126
	v_fmac_f32_e32 v153, v127, v127
	v_fmac_f32_e32 v153, v128, v128
	v_fmac_f32_e32 v153, v129, v129
	ds_swizzle_b32 v154, v146 offset:0x41f
	ds_swizzle_b32 v155, v147 offset:0x41f
	ds_swizzle_b32 v156, v148 offset:0x41f
	ds_swizzle_b32 v157, v149 offset:0x41f
	ds_swizzle_b32 v158, v150 offset:0x41f
	ds_swizzle_b32 v159, v151 offset:0x41f
	ds_swizzle_b32 v160, v152 offset:0x41f
	ds_swizzle_b32 v161, v153 offset:0x41f
	s_waitcnt lgkmcnt(0)
	v_add_f32_e32 v146, v146, v154
	v_add_f32_e32 v147, v147, v155
	v_add_f32_e32 v148, v148, v156
	v_add_f32_e32 v149, v149, v157
	v_add_f32_e32 v150, v150, v158
	v_add_f32_e32 v151, v151, v159
	v_add_f32_e32 v152, v152, v160
	v_add_f32_e32 v153, v153, v161
	s_nop 0
	ds_swizzle_b32 v154, v146 offset:0x81f
	ds_swizzle_b32 v155, v147 offset:0x81f
	ds_swizzle_b32 v156, v148 offset:0x81f
	ds_swizzle_b32 v157, v149 offset:0x81f
	ds_swizzle_b32 v158, v150 offset:0x81f
	ds_swizzle_b32 v159, v151 offset:0x81f
	ds_swizzle_b32 v160, v152 offset:0x81f
	ds_swizzle_b32 v161, v153 offset:0x81f
	s_waitcnt lgkmcnt(0)
	v_add_f32_e32 v146, v146, v154
	v_add_f32_e32 v147, v147, v155
	v_add_f32_e32 v148, v148, v156
	v_add_f32_e32 v149, v149, v157
	v_add_f32_e32 v150, v150, v158
	v_add_f32_e32 v151, v151, v159
	v_add_f32_e32 v152, v152, v160
	v_add_f32_e32 v153, v153, v161
	s_nop 0
	ds_swizzle_b32 v154, v146 offset:0x101f
	ds_swizzle_b32 v155, v147 offset:0x101f
	ds_swizzle_b32 v156, v148 offset:0x101f
	ds_swizzle_b32 v157, v149 offset:0x101f
	ds_swizzle_b32 v158, v150 offset:0x101f
	ds_swizzle_b32 v159, v151 offset:0x101f
	ds_swizzle_b32 v160, v152 offset:0x101f
	ds_swizzle_b32 v161, v153 offset:0x101f
	s_waitcnt lgkmcnt(0)
	v_add_f32_e32 v146, v146, v154
	v_add_f32_e32 v147, v147, v155
	v_add_f32_e32 v148, v148, v156
	v_add_f32_e32 v149, v149, v157
	v_add_f32_e32 v150, v150, v158
	v_add_f32_e32 v151, v151, v159
	v_add_f32_e32 v152, v152, v160
	v_add_f32_e32 v153, v153, v161
	s_nop 0
	ds_swizzle_b32 v154, v146 offset:0x201f
	ds_swizzle_b32 v155, v147 offset:0x201f
	ds_swizzle_b32 v156, v148 offset:0x201f
	ds_swizzle_b32 v157, v149 offset:0x201f
	ds_swizzle_b32 v158, v150 offset:0x201f
	ds_swizzle_b32 v159, v151 offset:0x201f
	ds_swizzle_b32 v160, v152 offset:0x201f
	ds_swizzle_b32 v161, v153 offset:0x201f
	s_waitcnt lgkmcnt(0)
	v_add_f32_e32 v146, v146, v154
	v_add_f32_e32 v147, v147, v155
	v_add_f32_e32 v148, v148, v156
	v_add_f32_e32 v149, v149, v157
	v_add_f32_e32 v150, v150, v158
	v_add_f32_e32 v151, v151, v159
	v_add_f32_e32 v152, v152, v160
	v_add_f32_e32 v153, v153, v161
	s_nop 0
	ds_swizzle_b32 v154, v146 offset:0x401f
	ds_swizzle_b32 v155, v147 offset:0x401f
	ds_swizzle_b32 v156, v148 offset:0x401f
	ds_swizzle_b32 v157, v149 offset:0x401f
	ds_swizzle_b32 v158, v150 offset:0x401f
	ds_swizzle_b32 v159, v151 offset:0x401f
	ds_swizzle_b32 v160, v152 offset:0x401f
	ds_swizzle_b32 v161, v153 offset:0x401f
	s_waitcnt lgkmcnt(0)
	v_add_f32_e32 v146, v146, v154
	v_add_f32_e32 v147, v147, v155
	v_add_f32_e32 v148, v148, v156
	v_add_f32_e32 v149, v149, v157
	v_add_f32_e32 v150, v150, v158
	v_add_f32_e32 v151, v151, v159
	v_add_f32_e32 v152, v152, v160
	v_add_f32_e32 v153, v153, v161
	s_nop 0
	ds_bpermute_b32 v154, v184, v146
	ds_bpermute_b32 v155, v184, v147
	ds_bpermute_b32 v156, v184, v148
	ds_bpermute_b32 v157, v184, v149
	ds_bpermute_b32 v158, v184, v150
	ds_bpermute_b32 v159, v184, v151
	ds_bpermute_b32 v160, v184, v152
	ds_bpermute_b32 v161, v184, v153
	s_waitcnt lgkmcnt(0)
	v_add_f32_e32 v146, v146, v154
	v_add_f32_e32 v147, v147, v155
	v_add_f32_e32 v148, v148, v156
	v_add_f32_e32 v149, v149, v157
	v_add_f32_e32 v150, v150, v158
	v_add_f32_e32 v151, v151, v159
	v_add_f32_e32 v152, v152, v160
	v_add_f32_e32 v153, v153, v161
	v_fmamk_f32 v146, v146, 0x3a800000, v167
	v_fmamk_f32 v147, v147, 0x3a800000, v167
	v_fmamk_f32 v148, v148, 0x3a800000, v167
	v_fmamk_f32 v149, v149, 0x3a800000, v167
	v_fmamk_f32 v150, v150, 0x3a800000, v167
	v_fmamk_f32 v151, v151, 0x3a800000, v167
	v_fmamk_f32 v152, v152, 0x3a800000, v167
	v_fmamk_f32 v153, v153, 0x3a800000, v167
	v_rsq_f32_e32 v146, v146
	v_rsq_f32_e32 v147, v147
	v_rsq_f32_e32 v148, v148
	v_rsq_f32_e32 v149, v149
	v_rsq_f32_e32 v150, v150
	v_rsq_f32_e32 v151, v151
	v_rsq_f32_e32 v152, v152
	v_rsq_f32_e32 v153, v153
	s_nop 0
	s_mov_b32 s6, s2
	s_mul_i32 s4, s2, 0x880
	s_add_u32 s4, s80, s4
	s_addc_u32 s5, s81, 0
	s_cmpk_ge_u32 s6, 0x4000
	s_cbranch_scc1 .Lr8_stp0
	v_mul_f32_e32 v154, v2, v146
	v_mul_f32_e32 v155, v3, v146
	v_mul_f32_e32 v156, v4, v146
	v_mul_f32_e32 v157, v5, v146
	v_mul_f32_e32 v154, v130, v154
	v_mul_f32_e32 v155, v131, v155
	v_mul_f32_e32 v156, v132, v156
	v_mul_f32_e32 v157, v133, v157
	v_cvt_pk_bf16_f32 v188, v154, v155
	v_cvt_pk_bf16_f32 v189, v156, v157
	global_store_dwordx2 v183, v[188:189], s[4:5] offset:0
	s_nop 0
	v_mul_f32_e32 v154, v6, v146
	v_mul_f32_e32 v155, v7, v146
	v_mul_f32_e32 v156, v8, v146
	v_mul_f32_e32 v157, v9, v146
	v_mul_f32_e32 v154, v134, v154
	v_mul_f32_e32 v155, v135, v155
	v_mul_f32_e32 v156, v136, v156
	v_mul_f32_e32 v157, v137, v157
	v_cvt_pk_bf16_f32 v188, v154, v155
	v_cvt_pk_bf16_f32 v189, v156, v157
	global_store_dwordx2 v183, v[188:189], s[4:5] offset:512
	s_nop 0
	v_mul_f32_e32 v154, v10, v146
	v_mul_f32_e32 v155, v11, v146
	v_mul_f32_e32 v156, v12, v146
	v_mul_f32_e32 v157, v13, v146
	v_mul_f32_e32 v154, v138, v154
	v_mul_f32_e32 v155, v139, v155
	v_mul_f32_e32 v156, v140, v156
	v_mul_f32_e32 v157, v141, v157
	v_cvt_pk_bf16_f32 v188, v154, v155
	v_cvt_pk_bf16_f32 v189, v156, v157
	global_store_dwordx2 v183, v[188:189], s[4:5] offset:1024
	s_nop 0
	v_mul_f32_e32 v154, v14, v146
	v_mul_f32_e32 v155, v15, v146
	v_mul_f32_e32 v156, v16, v146
	v_mul_f32_e32 v157, v17, v146
	v_mul_f32_e32 v154, v142, v154
	v_mul_f32_e32 v155, v143, v155
	v_mul_f32_e32 v156, v144, v156
	v_mul_f32_e32 v157, v145, v157
	v_cvt_pk_bf16_f32 v188, v154, v155
	v_cvt_pk_bf16_f32 v189, v156, v157
	global_store_dwordx2 v183, v[188:189], s[4:5] offset:1536
	s_nop 0
.Lr8_stp0:
	s_mul_i32 s7, s3, 0x880
	s_add_u32 s4, s4, s7
	s_addc_u32 s5, s5, 0
	s_add_i32 s6, s6, s3
	s_cmpk_ge_u32 s6, 0x4000
	s_cbranch_scc1 .Lr8_stp1
	v_mul_f32_e32 v154, v18, v147
	v_mul_f32_e32 v155, v19, v147
	v_mul_f32_e32 v156, v20, v147
	v_mul_f32_e32 v157, v21, v147
	v_mul_f32_e32 v154, v130, v154
	v_mul_f32_e32 v155, v131, v155
	v_mul_f32_e32 v156, v132, v156
	v_mul_f32_e32 v157, v133, v157
	v_cvt_pk_bf16_f32 v188, v154, v155
	v_cvt_pk_bf16_f32 v189, v156, v157
	global_store_dwordx2 v183, v[188:189], s[4:5] offset:0
	s_nop 0
	v_mul_f32_e32 v154, v22, v147
	v_mul_f32_e32 v155, v23, v147
	v_mul_f32_e32 v156, v24, v147
	v_mul_f32_e32 v157, v25, v147
	v_mul_f32_e32 v154, v134, v154
	v_mul_f32_e32 v155, v135, v155
	v_mul_f32_e32 v156, v136, v156
	v_mul_f32_e32 v157, v137, v157
	v_cvt_pk_bf16_f32 v188, v154, v155
	v_cvt_pk_bf16_f32 v189, v156, v157
	global_store_dwordx2 v183, v[188:189], s[4:5] offset:512
	s_nop 0
	v_mul_f32_e32 v154, v26, v147
	v_mul_f32_e32 v155, v27, v147
	v_mul_f32_e32 v156, v28, v147
	v_mul_f32_e32 v157, v29, v147
	v_mul_f32_e32 v154, v138, v154
	v_mul_f32_e32 v155, v139, v155
	v_mul_f32_e32 v156, v140, v156
	v_mul_f32_e32 v157, v141, v157
	v_cvt_pk_bf16_f32 v188, v154, v155
	v_cvt_pk_bf16_f32 v189, v156, v157
	global_store_dwordx2 v183, v[188:189], s[4:5] offset:1024
	s_nop 0
	v_mul_f32_e32 v154, v30, v147
	v_mul_f32_e32 v155, v31, v147
	v_mul_f32_e32 v156, v32, v147
	v_mul_f32_e32 v157, v33, v147
	v_mul_f32_e32 v154, v142, v154
	v_mul_f32_e32 v155, v143, v155
	v_mul_f32_e32 v156, v144, v156
	v_mul_f32_e32 v157, v145, v157
	v_cvt_pk_bf16_f32 v188, v154, v155
	v_cvt_pk_bf16_f32 v189, v156, v157
	global_store_dwordx2 v183, v[188:189], s[4:5] offset:1536
	s_nop 0
.Lr8_stp1:
	s_mul_i32 s7, s3, 0x880
	s_add_u32 s4, s4, s7
	s_addc_u32 s5, s5, 0
	s_add_i32 s6, s6, s3
	s_cmpk_ge_u32 s6, 0x4000
	s_cbranch_scc1 .Lr8_stp2
	v_mul_f32_e32 v154, v34, v148
	v_mul_f32_e32 v155, v35, v148
	v_mul_f32_e32 v156, v36, v148
	v_mul_f32_e32 v157, v37, v148
	v_mul_f32_e32 v154, v130, v154
	v_mul_f32_e32 v155, v131, v155
	v_mul_f32_e32 v156, v132, v156
	v_mul_f32_e32 v157, v133, v157
	v_cvt_pk_bf16_f32 v188, v154, v155
	v_cvt_pk_bf16_f32 v189, v156, v157
	global_store_dwordx2 v183, v[188:189], s[4:5] offset:0
	s_nop 0
	v_mul_f32_e32 v154, v38, v148
	v_mul_f32_e32 v155, v39, v148
	v_mul_f32_e32 v156, v40, v148
	v_mul_f32_e32 v157, v41, v148
	v_mul_f32_e32 v154, v134, v154
	v_mul_f32_e32 v155, v135, v155
	v_mul_f32_e32 v156, v136, v156
	v_mul_f32_e32 v157, v137, v157
	v_cvt_pk_bf16_f32 v188, v154, v155
	v_cvt_pk_bf16_f32 v189, v156, v157
	global_store_dwordx2 v183, v[188:189], s[4:5] offset:512
	s_nop 0
	v_mul_f32_e32 v154, v42, v148
	v_mul_f32_e32 v155, v43, v148
	v_mul_f32_e32 v156, v44, v148
	v_mul_f32_e32 v157, v45, v148
	v_mul_f32_e32 v154, v138, v154
	v_mul_f32_e32 v155, v139, v155
	v_mul_f32_e32 v156, v140, v156
	v_mul_f32_e32 v157, v141, v157
	v_cvt_pk_bf16_f32 v188, v154, v155
	v_cvt_pk_bf16_f32 v189, v156, v157
	global_store_dwordx2 v183, v[188:189], s[4:5] offset:1024
	s_nop 0
	v_mul_f32_e32 v154, v46, v148
	v_mul_f32_e32 v155, v47, v148
	v_mul_f32_e32 v156, v48, v148
	v_mul_f32_e32 v157, v49, v148
	v_mul_f32_e32 v154, v142, v154
	v_mul_f32_e32 v155, v143, v155
	v_mul_f32_e32 v156, v144, v156
	v_mul_f32_e32 v157, v145, v157
	v_cvt_pk_bf16_f32 v188, v154, v155
	v_cvt_pk_bf16_f32 v189, v156, v157
	global_store_dwordx2 v183, v[188:189], s[4:5] offset:1536
	s_nop 0
.Lr8_stp2:
	s_mul_i32 s7, s3, 0x880
	s_add_u32 s4, s4, s7
	s_addc_u32 s5, s5, 0
	s_add_i32 s6, s6, s3
	s_cmpk_ge_u32 s6, 0x4000
	s_cbranch_scc1 .Lr8_stp3
	v_mul_f32_e32 v154, v50, v149
	v_mul_f32_e32 v155, v51, v149
	v_mul_f32_e32 v156, v52, v149
	v_mul_f32_e32 v157, v53, v149
	v_mul_f32_e32 v154, v130, v154
	v_mul_f32_e32 v155, v131, v155
	v_mul_f32_e32 v156, v132, v156
	v_mul_f32_e32 v157, v133, v157
	v_cvt_pk_bf16_f32 v188, v154, v155
	v_cvt_pk_bf16_f32 v189, v156, v157
	global_store_dwordx2 v183, v[188:189], s[4:5] offset:0
	s_nop 0
	v_mul_f32_e32 v154, v54, v149
	v_mul_f32_e32 v155, v55, v149
	v_mul_f32_e32 v156, v56, v149
	v_mul_f32_e32 v157, v57, v149
	v_mul_f32_e32 v154, v134, v154
	v_mul_f32_e32 v155, v135, v155
	v_mul_f32_e32 v156, v136, v156
	v_mul_f32_e32 v157, v137, v157
	v_cvt_pk_bf16_f32 v188, v154, v155
	v_cvt_pk_bf16_f32 v189, v156, v157
	global_store_dwordx2 v183, v[188:189], s[4:5] offset:512
	s_nop 0
	v_mul_f32_e32 v154, v58, v149
	v_mul_f32_e32 v155, v59, v149
	v_mul_f32_e32 v156, v60, v149
	v_mul_f32_e32 v157, v61, v149
	v_mul_f32_e32 v154, v138, v154
	v_mul_f32_e32 v155, v139, v155
	v_mul_f32_e32 v156, v140, v156
	v_mul_f32_e32 v157, v141, v157
	v_cvt_pk_bf16_f32 v188, v154, v155
	v_cvt_pk_bf16_f32 v189, v156, v157
	global_store_dwordx2 v183, v[188:189], s[4:5] offset:1024
	s_nop 0
	v_mul_f32_e32 v154, v62, v149
	v_mul_f32_e32 v155, v63, v149
	v_mul_f32_e32 v156, v64, v149
	v_mul_f32_e32 v157, v65, v149
	v_mul_f32_e32 v154, v142, v154
	v_mul_f32_e32 v155, v143, v155
	v_mul_f32_e32 v156, v144, v156
	v_mul_f32_e32 v157, v145, v157
	v_cvt_pk_bf16_f32 v188, v154, v155
	v_cvt_pk_bf16_f32 v189, v156, v157
	global_store_dwordx2 v183, v[188:189], s[4:5] offset:1536
	s_nop 0
.Lr8_stp3:
	s_mul_i32 s7, s3, 0x880
	s_add_u32 s4, s4, s7
	s_addc_u32 s5, s5, 0
	s_add_i32 s6, s6, s3
	s_cmpk_ge_u32 s6, 0x4000
	s_cbranch_scc1 .Lr8_stp4
	v_mul_f32_e32 v154, v66, v150
	v_mul_f32_e32 v155, v67, v150
	v_mul_f32_e32 v156, v68, v150
	v_mul_f32_e32 v157, v69, v150
	v_mul_f32_e32 v154, v130, v154
	v_mul_f32_e32 v155, v131, v155
	v_mul_f32_e32 v156, v132, v156
	v_mul_f32_e32 v157, v133, v157
	v_cvt_pk_bf16_f32 v188, v154, v155
	v_cvt_pk_bf16_f32 v189, v156, v157
	global_store_dwordx2 v183, v[188:189], s[4:5] offset:0
	s_nop 0
	v_mul_f32_e32 v154, v70, v150
	v_mul_f32_e32 v155, v71, v150
	v_mul_f32_e32 v156, v72, v150
	v_mul_f32_e32 v157, v73, v150
	v_mul_f32_e32 v154, v134, v154
	v_mul_f32_e32 v155, v135, v155
	v_mul_f32_e32 v156, v136, v156
	v_mul_f32_e32 v157, v137, v157
	v_cvt_pk_bf16_f32 v188, v154, v155
	v_cvt_pk_bf16_f32 v189, v156, v157
	global_store_dwordx2 v183, v[188:189], s[4:5] offset:512
	s_nop 0
	v_mul_f32_e32 v154, v74, v150
	v_mul_f32_e32 v155, v75, v150
	v_mul_f32_e32 v156, v76, v150
	v_mul_f32_e32 v157, v77, v150
	v_mul_f32_e32 v154, v138, v154
	v_mul_f32_e32 v155, v139, v155
	v_mul_f32_e32 v156, v140, v156
	v_mul_f32_e32 v157, v141, v157
	v_cvt_pk_bf16_f32 v188, v154, v155
	v_cvt_pk_bf16_f32 v189, v156, v157
	global_store_dwordx2 v183, v[188:189], s[4:5] offset:1024
	s_nop 0
	v_mul_f32_e32 v154, v78, v150
	v_mul_f32_e32 v155, v79, v150
	v_mul_f32_e32 v156, v80, v150
	v_mul_f32_e32 v157, v81, v150
	v_mul_f32_e32 v154, v142, v154
	v_mul_f32_e32 v155, v143, v155
	v_mul_f32_e32 v156, v144, v156
	v_mul_f32_e32 v157, v145, v157
	v_cvt_pk_bf16_f32 v188, v154, v155
	v_cvt_pk_bf16_f32 v189, v156, v157
	global_store_dwordx2 v183, v[188:189], s[4:5] offset:1536
	s_nop 0
.Lr8_stp4:
	s_mul_i32 s7, s3, 0x880
	s_add_u32 s4, s4, s7
	s_addc_u32 s5, s5, 0
	s_add_i32 s6, s6, s3
	s_cmpk_ge_u32 s6, 0x4000
	s_cbranch_scc1 .Lr8_stp5
	v_mul_f32_e32 v154, v82, v151
	v_mul_f32_e32 v155, v83, v151
	v_mul_f32_e32 v156, v84, v151
	v_mul_f32_e32 v157, v85, v151
	v_mul_f32_e32 v154, v130, v154
	v_mul_f32_e32 v155, v131, v155
	v_mul_f32_e32 v156, v132, v156
	v_mul_f32_e32 v157, v133, v157
	v_cvt_pk_bf16_f32 v188, v154, v155
	v_cvt_pk_bf16_f32 v189, v156, v157
	global_store_dwordx2 v183, v[188:189], s[4:5] offset:0
	s_nop 0
	v_mul_f32_e32 v154, v86, v151
	v_mul_f32_e32 v155, v87, v151
	v_mul_f32_e32 v156, v88, v151
	v_mul_f32_e32 v157, v89, v151
	v_mul_f32_e32 v154, v134, v154
	v_mul_f32_e32 v155, v135, v155
	v_mul_f32_e32 v156, v136, v156
	v_mul_f32_e32 v157, v137, v157
	v_cvt_pk_bf16_f32 v188, v154, v155
	v_cvt_pk_bf16_f32 v189, v156, v157
	global_store_dwordx2 v183, v[188:189], s[4:5] offset:512
	s_nop 0
	v_mul_f32_e32 v154, v90, v151
	v_mul_f32_e32 v155, v91, v151
	v_mul_f32_e32 v156, v92, v151
	v_mul_f32_e32 v157, v93, v151
	v_mul_f32_e32 v154, v138, v154
	v_mul_f32_e32 v155, v139, v155
	v_mul_f32_e32 v156, v140, v156
	v_mul_f32_e32 v157, v141, v157
	v_cvt_pk_bf16_f32 v188, v154, v155
	v_cvt_pk_bf16_f32 v189, v156, v157
	global_store_dwordx2 v183, v[188:189], s[4:5] offset:1024
	s_nop 0
	v_mul_f32_e32 v154, v94, v151
	v_mul_f32_e32 v155, v95, v151
	v_mul_f32_e32 v156, v96, v151
	v_mul_f32_e32 v157, v97, v151
	v_mul_f32_e32 v154, v142, v154
	v_mul_f32_e32 v155, v143, v155
	v_mul_f32_e32 v156, v144, v156
	v_mul_f32_e32 v157, v145, v157
	v_cvt_pk_bf16_f32 v188, v154, v155
	v_cvt_pk_bf16_f32 v189, v156, v157
	global_store_dwordx2 v183, v[188:189], s[4:5] offset:1536
	s_nop 0
.Lr8_stp5:
	s_mul_i32 s7, s3, 0x880
	s_add_u32 s4, s4, s7
	s_addc_u32 s5, s5, 0
	s_add_i32 s6, s6, s3
	s_cmpk_ge_u32 s6, 0x4000
	s_cbranch_scc1 .Lr8_stp6
	v_mul_f32_e32 v154, v98, v152
	v_mul_f32_e32 v155, v99, v152
	v_mul_f32_e32 v156, v100, v152
	v_mul_f32_e32 v157, v101, v152
	v_mul_f32_e32 v154, v130, v154
	v_mul_f32_e32 v155, v131, v155
	v_mul_f32_e32 v156, v132, v156
	v_mul_f32_e32 v157, v133, v157
	v_cvt_pk_bf16_f32 v188, v154, v155
	v_cvt_pk_bf16_f32 v189, v156, v157
	global_store_dwordx2 v183, v[188:189], s[4:5] offset:0
	s_nop 0
	v_mul_f32_e32 v154, v102, v152
	v_mul_f32_e32 v155, v103, v152
	v_mul_f32_e32 v156, v104, v152
	v_mul_f32_e32 v157, v105, v152
	v_mul_f32_e32 v154, v134, v154
	v_mul_f32_e32 v155, v135, v155
	v_mul_f32_e32 v156, v136, v156
	v_mul_f32_e32 v157, v137, v157
	v_cvt_pk_bf16_f32 v188, v154, v155
	v_cvt_pk_bf16_f32 v189, v156, v157
	global_store_dwordx2 v183, v[188:189], s[4:5] offset:512
	s_nop 0
	v_mul_f32_e32 v154, v106, v152
	v_mul_f32_e32 v155, v107, v152
	v_mul_f32_e32 v156, v108, v152
	v_mul_f32_e32 v157, v109, v152
	v_mul_f32_e32 v154, v138, v154
	v_mul_f32_e32 v155, v139, v155
	v_mul_f32_e32 v156, v140, v156
	v_mul_f32_e32 v157, v141, v157
	v_cvt_pk_bf16_f32 v188, v154, v155
	v_cvt_pk_bf16_f32 v189, v156, v157
	global_store_dwordx2 v183, v[188:189], s[4:5] offset:1024
	s_nop 0
	v_mul_f32_e32 v154, v110, v152
	v_mul_f32_e32 v155, v111, v152
	v_mul_f32_e32 v156, v112, v152
	v_mul_f32_e32 v157, v113, v152
	v_mul_f32_e32 v154, v142, v154
	v_mul_f32_e32 v155, v143, v155
	v_mul_f32_e32 v156, v144, v156
	v_mul_f32_e32 v157, v145, v157
	v_cvt_pk_bf16_f32 v188, v154, v155
	v_cvt_pk_bf16_f32 v189, v156, v157
	global_store_dwordx2 v183, v[188:189], s[4:5] offset:1536
	s_nop 0
.Lr8_stp6:
	s_mul_i32 s7, s3, 0x880
	s_add_u32 s4, s4, s7
	s_addc_u32 s5, s5, 0
	s_add_i32 s6, s6, s3
	s_cmpk_ge_u32 s6, 0x4000
	s_cbranch_scc1 .Lr8_stp7
	v_mul_f32_e32 v154, v114, v153
	v_mul_f32_e32 v155, v115, v153
	v_mul_f32_e32 v156, v116, v153
	v_mul_f32_e32 v157, v117, v153
	v_mul_f32_e32 v154, v130, v154
	v_mul_f32_e32 v155, v131, v155
	v_mul_f32_e32 v156, v132, v156
	v_mul_f32_e32 v157, v133, v157
	v_cvt_pk_bf16_f32 v188, v154, v155
	v_cvt_pk_bf16_f32 v189, v156, v157
	global_store_dwordx2 v183, v[188:189], s[4:5] offset:0
	s_nop 0
	v_mul_f32_e32 v154, v118, v153
	v_mul_f32_e32 v155, v119, v153
	v_mul_f32_e32 v156, v120, v153
	v_mul_f32_e32 v157, v121, v153
	v_mul_f32_e32 v154, v134, v154
	v_mul_f32_e32 v155, v135, v155
	v_mul_f32_e32 v156, v136, v156
	v_mul_f32_e32 v157, v137, v157
	v_cvt_pk_bf16_f32 v188, v154, v155
	v_cvt_pk_bf16_f32 v189, v156, v157
	global_store_dwordx2 v183, v[188:189], s[4:5] offset:512
	s_nop 0
	v_mul_f32_e32 v154, v122, v153
	v_mul_f32_e32 v155, v123, v153
	v_mul_f32_e32 v156, v124, v153
	v_mul_f32_e32 v157, v125, v153
	v_mul_f32_e32 v154, v138, v154
	v_mul_f32_e32 v155, v139, v155
	v_mul_f32_e32 v156, v140, v156
	v_mul_f32_e32 v157, v141, v157
	v_cvt_pk_bf16_f32 v188, v154, v155
	v_cvt_pk_bf16_f32 v189, v156, v157
	global_store_dwordx2 v183, v[188:189], s[4:5] offset:1024
	s_nop 0
	v_mul_f32_e32 v154, v126, v153
	v_mul_f32_e32 v155, v127, v153
	v_mul_f32_e32 v156, v128, v153
	v_mul_f32_e32 v157, v129, v153
	v_mul_f32_e32 v154, v142, v154
	v_mul_f32_e32 v155, v143, v155
	v_mul_f32_e32 v156, v144, v156
	v_mul_f32_e32 v157, v145, v157
	v_cvt_pk_bf16_f32 v188, v154, v155
	v_cvt_pk_bf16_f32 v189, v156, v157
	global_store_dwordx2 v183, v[188:189], s[4:5] offset:1536
	s_nop 0
.Lr8_stp7:
.Lr8_next:
	s_mul_i32 s4, s3, 8
	s_add_i32 s2, s2, s4
	s_cmpk_lt_u32 s2, 0x4000
	s_cbranch_scc1 .Lr8_outer

.LBB0_523:
	s_or_b64 exec, exec, s[2:3]
	v_and_b32_e32 v185, 63, v163
	v_lshlrev_b32_e32 v182, 4, v185
	v_lshlrev_b32_e32 v183, 3, v185
	v_xor_b32_e32 v184, 32, v185
	v_lshlrev_b32_e32 v184, 2, v184
	v_lshrrev_b32_e32 v186, 6, v163
	v_readlane_b32 s2, v235, 26
	v_readlane_b32 s3, v235, 27
	global_load_dword v185, v[164:165], off
	s_nop 3
	global_load_dwordx4 v[130:133], v182, s[2:3] offset:0
	global_load_dwordx4 v[134:137], v182, s[2:3] offset:1024
	global_load_dwordx4 v[138:141], v182, s[2:3] offset:2048
	global_load_dwordx4 v[142:145], v182, s[2:3] offset:3072
	v_readlane_b32 s2, v237, 0
	v_readfirstlane_b32 s3, v186
	s_lshl_b32 s2, s2, 2
	s_add_i32 s2, s2, s3
	s_waitcnt vmcnt(4)
	v_readfirstlane_b32 s3, v185
	s_lshl_b32 s3, s3, 2
.Lr0_outer:
	v_readlane_b32 s0, v235, 24
	v_readlane_b32 s1, v235, 25
	s_lshl_b32 s4, s2, 12
	s_add_u32 s0, s0, s4
	s_addc_u32 s1, s1, 0
	s_mov_b32 s6, s2
	s_cmpk_ge_u32 s6, 0x4000
	s_cbranch_scc1 .Lr0_ld0
	global_load_dwordx4 v[2:5], v182, s[0:1] offset:0
	global_load_dwordx4 v[6:9], v182, s[0:1] offset:1024
	global_load_dwordx4 v[10:13], v182, s[0:1] offset:2048
	global_load_dwordx4 v[14:17], v182, s[0:1] offset:3072

.Lr0_ld7:
	s_waitcnt vmcnt(0)
	v_mul_f32_e32 v146, v2, v2
	v_fmac_f32_e32 v146, v3, v3
	v_fmac_f32_e32 v146, v4, v4
	v_fmac_f32_e32 v146, v5, v5
	v_fmac_f32_e32 v146, v6, v6
	v_fmac_f32_e32 v146, v7, v7
	v_fmac_f32_e32 v146, v8, v8
	v_fmac_f32_e32 v146, v9, v9
	v_fmac_f32_e32 v146, v10, v10
	v_fmac_f32_e32 v146, v11, v11
	v_fmac_f32_e32 v146, v12, v12
	v_fmac_f32_e32 v146, v13, v13
	v_fmac_f32_e32 v146, v14, v14
	v_fmac_f32_e32 v146, v15, v15
	v_fmac_f32_e32 v146, v16, v16
	v_fmac_f32_e32 v146, v17, v17
	v_mul_f32_e32 v147, v18, v18
	v_fmac_f32_e32 v147, v19, v19
	v_fmac_f32_e32 v147, v20, v20
	v_fmac_f32_e32 v147, v21, v21
	v_fmac_f32_e32 v147, v22, v22
	v_fmac_f32_e32 v147, v23, v23
	v_fmac_f32_e32 v147, v24, v24
	v_fmac_f32_e32 v147, v25, v25
	v_fmac_f32_e32 v147, v26, v26
	v_fmac_f32_e32 v147, v27, v27
	v_fmac_f32_e32 v147, v28, v28
	v_fmac_f32_e32 v147, v29, v29
	v_fmac_f32_e32 v147, v30, v30
	v_fmac_f32_e32 v147, v31, v31
	v_fmac_f32_e32 v147, v32, v32
	v_fmac_f32_e32 v147, v33, v33
	v_mul_f32_e32 v148, v34, v34
	v_fmac_f32_e32 v148, v35, v35
	v_fmac_f32_e32 v148, v36, v36
	v_fmac_f32_e32 v148, v37, v37
	v_fmac_f32_e32 v148, v38, v38
	v_fmac_f32_e32 v148, v39, v39
	v_fmac_f32_e32 v148, v40, v40
	v_fmac_f32_e32 v148, v41, v41
	v_fmac_f32_e32 v148, v42, v42
	v_fmac_f32_e32 v148, v43, v43
	v_fmac_f32_e32 v148, v44, v44
	v_fmac_f32_e32 v148, v45, v45
	v_fmac_f32_e32 v148, v46, v46
	v_fmac_f32_e32 v148, v47, v47
	v_fmac_f32_e32 v148, v48, v48
	v_fmac_f32_e32 v148, v49, v49
	v_mul_f32_e32 v149, v50, v50
	v_fmac_f32_e32 v149, v51, v51
	v_fmac_f32_e32 v149, v52, v52
	v_fmac_f32_e32 v149, v53, v53
	v_fmac_f32_e32 v149, v54, v54
	v_fmac_f32_e32 v149, v55, v55
	v_fmac_f32_e32 v149, v56, v56
	v_fmac_f32_e32 v149, v57, v57
	v_fmac_f32_e32 v149, v58, v58
	v_fmac_f32_e32 v149, v59, v59
	v_fmac_f32_e32 v149, v60, v60
	v_fmac_f32_e32 v149, v61, v61
	v_fmac_f32_e32 v149, v62, v62
	v_fmac_f32_e32 v149, v63, v63
	v_fmac_f32_e32 v149, v64, v64
	v_fmac_f32_e32 v149, v65, v65
	v_mul_f32_e32 v150, v66, v66
	v_fmac_f32_e32 v150, v67, v67
	v_fmac_f32_e32 v150, v68, v68
	v_fmac_f32_e32 v150, v69, v69
	v_fmac_f32_e32 v150, v70, v70
	v_fmac_f32_e32 v150, v71, v71
	v_fmac_f32_e32 v150, v72, v72
	v_fmac_f32_e32 v150, v73, v73
	v_fmac_f32_e32 v150, v74, v74
	v_fmac_f32_e32 v150, v75, v75
	v_fmac_f32_e32 v150, v76, v76
	v_fmac_f32_e32 v150, v77, v77
	v_fmac_f32_e32 v150, v78, v78
	v_fmac_f32_e32 v150, v79, v79
	v_fmac_f32_e32 v150, v80, v80
	v_fmac_f32_e32 v150, v81, v81
	v_mul_f32_e32 v151, v82, v82
	v_fmac_f32_e32 v151, v83, v83
	v_fmac_f32_e32 v151, v84, v84
	v_fmac_f32_e32 v151, v85, v85
	v_fmac_f32_e32 v151, v86, v86
	v_fmac_f32_e32 v151, v87, v87
	v_fmac_f32_e32 v151, v88, v88
	v_fmac_f32_e32 v151, v89, v89
	v_fmac_f32_e32 v151, v90, v90
	v_fmac_f32_e32 v151, v91, v91
	v_fmac_f32_e32 v151, v92, v92
	v_fmac_f32_e32 v151, v93, v93
	v_fmac_f32_e32 v151, v94, v94
	v_fmac_f32_e32 v151, v95, v95
	v_fmac_f32_e32 v151, v96, v96
	v_fmac_f32_e32 v151, v97, v97
	v_mul_f32_e32 v152, v98, v98
	v_fmac_f32_e32 v152, v99, v99
	v_fmac_f32_e32 v152, v100, v100
	v_fmac_f32_e32 v152, v101, v101
	v_fmac_f32_e32 v152, v102, v102
	v_fmac_f32_e32 v152, v103, v103
	v_fmac_f32_e32 v152, v104, v104
	v_fmac_f32_e32 v152, v105, v105
	v_fmac_f32_e32 v152, v106, v106
	v_fmac_f32_e32 v152, v107, v107
	v_fmac_f32_e32 v152, v108, v108
	v_fmac_f32_e32 v152, v109, v109
	v_fmac_f32_e32 v152, v110, v110
	v_fmac_f32_e32 v152, v111, v111
	v_fmac_f32_e32 v152, v112, v112
	v_fmac_f32_e32 v152, v113, v113
	v_mul_f32_e32 v153, v114, v114
	v_fmac_f32_e32 v153, v115, v115
	v_fmac_f32_e32 v153, v116, v116
	v_fmac_f32_e32 v153, v117, v117
	v_fmac_f32_e32 v153, v118, v118
	v_fmac_f32_e32 v153, v119, v119
	v_fmac_f32_e32 v153, v120, v120
	v_fmac_f32_e32 v153, v121, v121
	v_fmac_f32_e32 v153, v122, v122
	v_fmac_f32_e32 v153, v123, v123
	v_fmac_f32_e32 v153, v124, v124
	v_fmac_f32_e32 v153, v125, v125
	v_fmac_f32_e32 v153, v126, v126
	v_fmac_f32_e32 v153, v127, v127
	v_fmac_f32_e32 v153, v128, v128
	v_fmac_f32_e32 v153, v129, v129
	ds_swizzle_b32 v154, v146 offset:0x41f
	ds_swizzle_b32 v155, v147 offset:0x41f
	ds_swizzle_b32 v156, v148 offset:0x41f
	ds_swizzle_b32 v157, v149 offset:0x41f
	ds_swizzle_b32 v158, v150 offset:0x41f
	ds_swizzle_b32 v159, v151 offset:0x41f
	ds_swizzle_b32 v160, v152 offset:0x41f
	ds_swizzle_b32 v161, v153 offset:0x41f
	s_waitcnt lgkmcnt(0)
	v_add_f32_e32 v146, v146, v154
	v_add_f32_e32 v147, v147, v155
	v_add_f32_e32 v148, v148, v156
	v_add_f32_e32 v149, v149, v157
	v_add_f32_e32 v150, v150, v158
	v_add_f32_e32 v151, v151, v159
	v_add_f32_e32 v152, v152, v160
	v_add_f32_e32 v153, v153, v161
	s_nop 0
	ds_swizzle_b32 v154, v146 offset:0x81f
	ds_swizzle_b32 v155, v147 offset:0x81f
	ds_swizzle_b32 v156, v148 offset:0x81f
	ds_swizzle_b32 v157, v149 offset:0x81f
	ds_swizzle_b32 v158, v150 offset:0x81f
	ds_swizzle_b32 v159, v151 offset:0x81f
	ds_swizzle_b32 v160, v152 offset:0x81f
	ds_swizzle_b32 v161, v153 offset:0x81f
	s_waitcnt lgkmcnt(0)
	v_add_f32_e32 v146, v146, v154
	v_add_f32_e32 v147, v147, v155
	v_add_f32_e32 v148, v148, v156
	v_add_f32_e32 v149, v149, v157
	v_add_f32_e32 v150, v150, v158
	v_add_f32_e32 v151, v151, v159
	v_add_f32_e32 v152, v152, v160
	v_add_f32_e32 v153, v153, v161
	s_nop 0
	ds_swizzle_b32 v154, v146 offset:0x101f
	ds_swizzle_b32 v155, v147 offset:0x101f
	ds_swizzle_b32 v156, v148 offset:0x101f
	ds_swizzle_b32 v157, v149 offset:0x101f
	ds_swizzle_b32 v158, v150 offset:0x101f
	ds_swizzle_b32 v159, v151 offset:0x101f
	ds_swizzle_b32 v160, v152 offset:0x101f
	ds_swizzle_b32 v161, v153 offset:0x101f
	s_waitcnt lgkmcnt(0)
	v_add_f32_e32 v146, v146, v154
	v_add_f32_e32 v147, v147, v155
	v_add_f32_e32 v148, v148, v156
	v_add_f32_e32 v149, v149, v157
	v_add_f32_e32 v150, v150, v158
	v_add_f32_e32 v151, v151, v159
	v_add_f32_e32 v152, v152, v160
	v_add_f32_e32 v153, v153, v161
	s_nop 0
	ds_swizzle_b32 v154, v146 offset:0x201f
	ds_swizzle_b32 v155, v147 offset:0x201f
	ds_swizzle_b32 v156, v148 offset:0x201f
	ds_swizzle_b32 v157, v149 offset:0x201f
	ds_swizzle_b32 v158, v150 offset:0x201f
	ds_swizzle_b32 v159, v151 offset:0x201f
	ds_swizzle_b32 v160, v152 offset:0x201f
	ds_swizzle_b32 v161, v153 offset:0x201f
	s_waitcnt lgkmcnt(0)
	v_add_f32_e32 v146, v146, v154
	v_add_f32_e32 v147, v147, v155
	v_add_f32_e32 v148, v148, v156
	v_add_f32_e32 v149, v149, v157
	v_add_f32_e32 v150, v150, v158
	v_add_f32_e32 v151, v151, v159
	v_add_f32_e32 v152, v152, v160
	v_add_f32_e32 v153, v153, v161
	s_nop 0
	ds_swizzle_b32 v154, v146 offset:0x401f
	ds_swizzle_b32 v155, v147 offset:0x401f
	ds_swizzle_b32 v156, v148 offset:0x401f
	ds_swizzle_b32 v157, v149 offset:0x401f
	ds_swizzle_b32 v158, v150 offset:0x401f
	ds_swizzle_b32 v159, v151 offset:0x401f
	ds_swizzle_b32 v160, v152 offset:0x401f
	ds_swizzle_b32 v161, v153 offset:0x401f
	s_waitcnt lgkmcnt(0)
	v_add_f32_e32 v146, v146, v154
	v_add_f32_e32 v147, v147, v155
	v_add_f32_e32 v148, v148, v156
	v_add_f32_e32 v149, v149, v157
	v_add_f32_e32 v150, v150, v158
	v_add_f32_e32 v151, v151, v159
	v_add_f32_e32 v152, v152, v160
	v_add_f32_e32 v153, v153, v161
	s_nop 0
	ds_bpermute_b32 v154, v184, v146
	ds_bpermute_b32 v155, v184, v147
	ds_bpermute_b32 v156, v184, v148
	ds_bpermute_b32 v157, v184, v149
	ds_bpermute_b32 v158, v184, v150
	ds_bpermute_b32 v159, v184, v151
	ds_bpermute_b32 v160, v184, v152
	ds_bpermute_b32 v161, v184, v153
	s_waitcnt lgkmcnt(0)
	v_add_f32_e32 v146, v146, v154
	v_add_f32_e32 v147, v147, v155
	v_add_f32_e32 v148, v148, v156
	v_add_f32_e32 v149, v149, v157
	v_add_f32_e32 v150, v150, v158
	v_add_f32_e32 v151, v151, v159
	v_add_f32_e32 v152, v152, v160
	v_add_f32_e32 v153, v153, v161
	v_fmamk_f32 v146, v146, 0x3a800000, v167
	v_fmamk_f32 v147, v147, 0x3a800000, v167
	v_fmamk_f32 v148, v148, 0x3a800000, v167
	v_fmamk_f32 v149, v149, 0x3a800000, v167
	v_fmamk_f32 v150, v150, 0x3a800000, v167
	v_fmamk_f32 v151, v151, 0x3a800000, v167
	v_fmamk_f32 v152, v152, 0x3a800000, v167
	v_fmamk_f32 v153, v153, 0x3a800000, v167
	v_rsq_f32_e32 v146, v146
	v_rsq_f32_e32 v147, v147
	v_rsq_f32_e32 v148, v148
	v_rsq_f32_e32 v149, v149
	v_rsq_f32_e32 v150, v150
	v_rsq_f32_e32 v151, v151
	v_rsq_f32_e32 v152, v152
	v_rsq_f32_e32 v153, v153
	s_nop 0
	v_readlane_b32 s0, v235, 28
	v_readlane_b32 s1, v235, 29
	s_cmp_eq_u64 s[0:1], 0
	s_cbranch_scc1 .Lr0_plain
	s_mov_b32 s6, s2
	s_mul_i32 s4, s2, 0x880
	s_add_u32 s4, s80, s4
	s_addc_u32 s5, s81, 0
	s_lshl_b32 s7, s2, 12
	s_add_u32 s0, s0, s7
	s_addc_u32 s1, s1, 0
	s_cmpk_ge_u32 s6, 0x4000
	s_cbranch_scc1 .Lr0_stx0
	global_store_dwordx4 v182, v[2:5], s[0:1] offset:0
	global_store_dwordx4 v182, v[6:9], s[0:1] offset:1024
	global_store_dwordx4 v182, v[10:13], s[0:1] offset:2048
	global_store_dwordx4 v182, v[14:17], s[0:1] offset:3072
	v_mul_f32_e32 v154, v2, v146
	v_mul_f32_e32 v155, v3, v146
	v_mul_f32_e32 v156, v4, v146
	v_mul_f32_e32 v157, v5, v146
	v_mul_f32_e32 v154, v130, v154
	v_mul_f32_e32 v155, v131, v155
	v_mul_f32_e32 v156, v132, v156
	v_mul_f32_e32 v157, v133, v157
	v_cvt_pk_bf16_f32 v188, v154, v155
	v_cvt_pk_bf16_f32 v189, v156, v157
	global_store_dwordx2 v183, v[188:189], s[4:5] offset:0
	s_nop 0
	v_mul_f32_e32 v154, v6, v146
	v_mul_f32_e32 v155, v7, v146
	v_mul_f32_e32 v156, v8, v146
	v_mul_f32_e32 v157, v9, v146
	v_mul_f32_e32 v154, v134, v154
	v_mul_f32_e32 v155, v135, v155
	v_mul_f32_e32 v156, v136, v156
	v_mul_f32_e32 v157, v137, v157
	v_cvt_pk_bf16_f32 v188, v154, v155
	v_cvt_pk_bf16_f32 v189, v156, v157
	global_store_dwordx2 v183, v[188:189], s[4:5] offset:512
	s_nop 0
	v_mul_f32_e32 v154, v10, v146
	v_mul_f32_e32 v155, v11, v146
	v_mul_f32_e32 v156, v12, v146
	v_mul_f32_e32 v157, v13, v146
	v_mul_f32_e32 v154, v138, v154
	v_mul_f32_e32 v155, v139, v155
	v_mul_f32_e32 v156, v140, v156
	v_mul_f32_e32 v157, v141, v157
	v_cvt_pk_bf16_f32 v188, v154, v155
	v_cvt_pk_bf16_f32 v189, v156, v157
	global_store_dwordx2 v183, v[188:189], s[4:5] offset:1024
	s_nop 0
	v_mul_f32_e32 v154, v14, v146
	v_mul_f32_e32 v155, v15, v146
	v_mul_f32_e32 v156, v16, v146
	v_mul_f32_e32 v157, v17, v146
	v_mul_f32_e32 v154, v142, v154
	v_mul_f32_e32 v155, v143, v155
	v_mul_f32_e32 v156, v144, v156
	v_mul_f32_e32 v157, v145, v157
	v_cvt_pk_bf16_f32 v188, v154, v155
	v_cvt_pk_bf16_f32 v189, v156, v157
	global_store_dwordx2 v183, v[188:189], s[4:5] offset:1536
	s_nop 0
.Lr0_stx0:
	s_mul_i32 s7, s3, 0x880
	s_add_u32 s4, s4, s7
	s_addc_u32 s5, s5, 0
	s_lshl_b32 s7, s3, 12
	s_add_u32 s0, s0, s7
	s_addc_u32 s1, s1, 0
	s_add_i32 s6, s6, s3
	s_cmpk_ge_u32 s6, 0x4000
	s_cbranch_scc1 .Lr0_stx1
	global_store_dwordx4 v182, v[18:21], s[0:1] offset:0
	global_store_dwordx4 v182, v[22:25], s[0:1] offset:1024
	global_store_dwordx4 v182, v[26:29], s[0:1] offset:2048
	global_store_dwordx4 v182, v[30:33], s[0:1] offset:3072
	v_mul_f32_e32 v154, v18, v147
	v_mul_f32_e32 v155, v19, v147
	v_mul_f32_e32 v156, v20, v147
	v_mul_f32_e32 v157, v21, v147
	v_mul_f32_e32 v154, v130, v154
	v_mul_f32_e32 v155, v131, v155
	v_mul_f32_e32 v156, v132, v156
	v_mul_f32_e32 v157, v133, v157
	v_cvt_pk_bf16_f32 v188, v154, v155
	v_cvt_pk_bf16_f32 v189, v156, v157
	global_store_dwordx2 v183, v[188:189], s[4:5] offset:0
	s_nop 0
	v_mul_f32_e32 v154, v22, v147
	v_mul_f32_e32 v155, v23, v147
	v_mul_f32_e32 v156, v24, v147
	v_mul_f32_e32 v157, v25, v147
	v_mul_f32_e32 v154, v134, v154
	v_mul_f32_e32 v155, v135, v155
	v_mul_f32_e32 v156, v136, v156
	v_mul_f32_e32 v157, v137, v157
	v_cvt_pk_bf16_f32 v188, v154, v155
	v_cvt_pk_bf16_f32 v189, v156, v157
	global_store_dwordx2 v183, v[188:189], s[4:5] offset:512
	s_nop 0
	v_mul_f32_e32 v154, v26, v147
	v_mul_f32_e32 v155, v27, v147
	v_mul_f32_e32 v156, v28, v147
	v_mul_f32_e32 v157, v29, v147
	v_mul_f32_e32 v154, v138, v154
	v_mul_f32_e32 v155, v139, v155
	v_mul_f32_e32 v156, v140, v156
	v_mul_f32_e32 v157, v141, v157
	v_cvt_pk_bf16_f32 v188, v154, v155
	v_cvt_pk_bf16_f32 v189, v156, v157
	global_store_dwordx2 v183, v[188:189], s[4:5] offset:1024
	s_nop 0
	v_mul_f32_e32 v154, v30, v147
	v_mul_f32_e32 v155, v31, v147
	v_mul_f32_e32 v156, v32, v147
	v_mul_f32_e32 v157, v33, v147
	v_mul_f32_e32 v154, v142, v154
	v_mul_f32_e32 v155, v143, v155
	v_mul_f32_e32 v156, v144, v156
	v_mul_f32_e32 v157, v145, v157
	v_cvt_pk_bf16_f32 v188, v154, v155
	v_cvt_pk_bf16_f32 v189, v156, v157
	global_store_dwordx2 v183, v[188:189], s[4:5] offset:1536
	s_nop 0
.Lr0_stx1:
	s_mul_i32 s7, s3, 0x880
	s_add_u32 s4, s4, s7
	s_addc_u32 s5, s5, 0
	s_lshl_b32 s7, s3, 12
	s_add_u32 s0, s0, s7
	s_addc_u32 s1, s1, 0
	s_add_i32 s6, s6, s3
	s_cmpk_ge_u32 s6, 0x4000
	s_cbranch_scc1 .Lr0_stx2
	global_store_dwordx4 v182, v[34:37], s[0:1] offset:0
	global_store_dwordx4 v182, v[38:41], s[0:1] offset:1024
	global_store_dwordx4 v182, v[42:45], s[0:1] offset:2048
	global_store_dwordx4 v182, v[46:49], s[0:1] offset:3072
	v_mul_f32_e32 v154, v34, v148
	v_mul_f32_e32 v155, v35, v148
	v_mul_f32_e32 v156, v36, v148
	v_mul_f32_e32 v157, v37, v148
	v_mul_f32_e32 v154, v130, v154
	v_mul_f32_e32 v155, v131, v155
	v_mul_f32_e32 v156, v132, v156
	v_mul_f32_e32 v157, v133, v157
	v_cvt_pk_bf16_f32 v188, v154, v155
	v_cvt_pk_bf16_f32 v189, v156, v157
	global_store_dwordx2 v183, v[188:189], s[4:5] offset:0
	s_nop 0
	v_mul_f32_e32 v154, v38, v148
	v_mul_f32_e32 v155, v39, v148
	v_mul_f32_e32 v156, v40, v148
	v_mul_f32_e32 v157, v41, v148
	v_mul_f32_e32 v154, v134, v154
	v_mul_f32_e32 v155, v135, v155
	v_mul_f32_e32 v156, v136, v156
	v_mul_f32_e32 v157, v137, v157
	v_cvt_pk_bf16_f32 v188, v154, v155
	v_cvt_pk_bf16_f32 v189, v156, v157
	global_store_dwordx2 v183, v[188:189], s[4:5] offset:512
	s_nop 0
	v_mul_f32_e32 v154, v42, v148
	v_mul_f32_e32 v155, v43, v148
	v_mul_f32_e32 v156, v44, v148
	v_mul_f32_e32 v157, v45, v148
	v_mul_f32_e32 v154, v138, v154
	v_mul_f32_e32 v155, v139, v155
	v_mul_f32_e32 v156, v140, v156
	v_mul_f32_e32 v157, v141, v157
	v_cvt_pk_bf16_f32 v188, v154, v155
	v_cvt_pk_bf16_f32 v189, v156, v157
	global_store_dwordx2 v183, v[188:189], s[4:5] offset:1024
	s_nop 0
	v_mul_f32_e32 v154, v46, v148
	v_mul_f32_e32 v155, v47, v148
	v_mul_f32_e32 v156, v48, v148
	v_mul_f32_e32 v157, v49, v148
	v_mul_f32_e32 v154, v142, v154
	v_mul_f32_e32 v155, v143, v155
	v_mul_f32_e32 v156, v144, v156
	v_mul_f32_e32 v157, v145, v157
	v_cvt_pk_bf16_f32 v188, v154, v155
	v_cvt_pk_bf16_f32 v189, v156, v157
	global_store_dwordx2 v183, v[188:189], s[4:5] offset:1536
	s_nop 0
.Lr0_stx2:
	s_mul_i32 s7, s3, 0x880
	s_add_u32 s4, s4, s7
	s_addc_u32 s5, s5, 0
	s_lshl_b32 s7, s3, 12
	s_add_u32 s0, s0, s7
	s_addc_u32 s1, s1, 0
	s_add_i32 s6, s6, s3
	s_cmpk_ge_u32 s6, 0x4000
	s_cbranch_scc1 .Lr0_stx3
	global_store_dwordx4 v182, v[50:53], s[0:1] offset:0
	global_store_dwordx4 v182, v[54:57], s[0:1] offset:1024
	global_store_dwordx4 v182, v[58:61], s[0:1] offset:2048
	global_store_dwordx4 v182, v[62:65], s[0:1] offset:3072
	v_mul_f32_e32 v154, v50, v149
	v_mul_f32_e32 v155, v51, v149
	v_mul_f32_e32 v156, v52, v149
	v_mul_f32_e32 v157, v53, v149
	v_mul_f32_e32 v154, v130, v154
	v_mul_f32_e32 v155, v131, v155
	v_mul_f32_e32 v156, v132, v156
	v_mul_f32_e32 v157, v133, v157
	v_cvt_pk_bf16_f32 v188, v154, v155
	v_cvt_pk_bf16_f32 v189, v156, v157
	global_store_dwordx2 v183, v[188:189], s[4:5] offset:0
	s_nop 0
	v_mul_f32_e32 v154, v54, v149
	v_mul_f32_e32 v155, v55, v149
	v_mul_f32_e32 v156, v56, v149
	v_mul_f32_e32 v157, v57, v149
	v_mul_f32_e32 v154, v134, v154
	v_mul_f32_e32 v155, v135, v155
	v_mul_f32_e32 v156, v136, v156
	v_mul_f32_e32 v157, v137, v157
	v_cvt_pk_bf16_f32 v188, v154, v155
	v_cvt_pk_bf16_f32 v189, v156, v157
	global_store_dwordx2 v183, v[188:189], s[4:5] offset:512
	s_nop 0
	v_mul_f32_e32 v154, v58, v149
	v_mul_f32_e32 v155, v59, v149
	v_mul_f32_e32 v156, v60, v149
	v_mul_f32_e32 v157, v61, v149
	v_mul_f32_e32 v154, v138, v154
	v_mul_f32_e32 v155, v139, v155
	v_mul_f32_e32 v156, v140, v156
	v_mul_f32_e32 v157, v141, v157
	v_cvt_pk_bf16_f32 v188, v154, v155
	v_cvt_pk_bf16_f32 v189, v156, v157
	global_store_dwordx2 v183, v[188:189], s[4:5] offset:1024
	s_nop 0
	v_mul_f32_e32 v154, v62, v149
	v_mul_f32_e32 v155, v63, v149
	v_mul_f32_e32 v156, v64, v149
	v_mul_f32_e32 v157, v65, v149
	v_mul_f32_e32 v154, v142, v154
	v_mul_f32_e32 v155, v143, v155
	v_mul_f32_e32 v156, v144, v156
	v_mul_f32_e32 v157, v145, v157
	v_cvt_pk_bf16_f32 v188, v154, v155
	v_cvt_pk_bf16_f32 v189, v156, v157
	global_store_dwordx2 v183, v[188:189], s[4:5] offset:1536
	s_nop 0
.Lr0_stx3:
	s_mul_i32 s7, s3, 0x880
	s_add_u32 s4, s4, s7
	s_addc_u32 s5, s5, 0
	s_lshl_b32 s7, s3, 12
	s_add_u32 s0, s0, s7
	s_addc_u32 s1, s1, 0
	s_add_i32 s6, s6, s3
	s_cmpk_ge_u32 s6, 0x4000
	s_cbranch_scc1 .Lr0_stx4
	global_store_dwordx4 v182, v[66:69], s[0:1] offset:0
	global_store_dwordx4 v182, v[70:73], s[0:1] offset:1024
	global_store_dwordx4 v182, v[74:77], s[0:1] offset:2048
	global_store_dwordx4 v182, v[78:81], s[0:1] offset:3072
	v_mul_f32_e32 v154, v66, v150
	v_mul_f32_e32 v155, v67, v150
	v_mul_f32_e32 v156, v68, v150
	v_mul_f32_e32 v157, v69, v150
	v_mul_f32_e32 v154, v130, v154
	v_mul_f32_e32 v155, v131, v155
	v_mul_f32_e32 v156, v132, v156
	v_mul_f32_e32 v157, v133, v157
	v_cvt_pk_bf16_f32 v188, v154, v155
	v_cvt_pk_bf16_f32 v189, v156, v157
	global_store_dwordx2 v183, v[188:189], s[4:5] offset:0
	s_nop 0
	v_mul_f32_e32 v154, v70, v150
	v_mul_f32_e32 v155, v71, v150
	v_mul_f32_e32 v156, v72, v150
	v_mul_f32_e32 v157, v73, v150
	v_mul_f32_e32 v154, v134, v154
	v_mul_f32_e32 v155, v135, v155
	v_mul_f32_e32 v156, v136, v156
	v_mul_f32_e32 v157, v137, v157
	v_cvt_pk_bf16_f32 v188, v154, v155
	v_cvt_pk_bf16_f32 v189, v156, v157
	global_store_dwordx2 v183, v[188:189], s[4:5] offset:512
	s_nop 0
	v_mul_f32_e32 v154, v74, v150
	v_mul_f32_e32 v155, v75, v150
	v_mul_f32_e32 v156, v76, v150
	v_mul_f32_e32 v157, v77, v150
	v_mul_f32_e32 v154, v138, v154
	v_mul_f32_e32 v155, v139, v155
	v_mul_f32_e32 v156, v140, v156
	v_mul_f32_e32 v157, v141, v157
	v_cvt_pk_bf16_f32 v188, v154, v155
	v_cvt_pk_bf16_f32 v189, v156, v157
	global_store_dwordx2 v183, v[188:189], s[4:5] offset:1024
	s_nop 0
	v_mul_f32_e32 v154, v78, v150
	v_mul_f32_e32 v155, v79, v150
	v_mul_f32_e32 v156, v80, v150
	v_mul_f32_e32 v157, v81, v150
	v_mul_f32_e32 v154, v142, v154
	v_mul_f32_e32 v155, v143, v155
	v_mul_f32_e32 v156, v144, v156
	v_mul_f32_e32 v157, v145, v157
	v_cvt_pk_bf16_f32 v188, v154, v155
	v_cvt_pk_bf16_f32 v189, v156, v157
	global_store_dwordx2 v183, v[188:189], s[4:5] offset:1536
	s_nop 0
.Lr0_stx4:
	s_mul_i32 s7, s3, 0x880
	s_add_u32 s4, s4, s7
	s_addc_u32 s5, s5, 0
	s_lshl_b32 s7, s3, 12
	s_add_u32 s0, s0, s7
	s_addc_u32 s1, s1, 0
	s_add_i32 s6, s6, s3
	s_cmpk_ge_u32 s6, 0x4000
	s_cbranch_scc1 .Lr0_stx5
	global_store_dwordx4 v182, v[82:85], s[0:1] offset:0
	global_store_dwordx4 v182, v[86:89], s[0:1] offset:1024
	global_store_dwordx4 v182, v[90:93], s[0:1] offset:2048
	global_store_dwordx4 v182, v[94:97], s[0:1] offset:3072
	v_mul_f32_e32 v154, v82, v151
	v_mul_f32_e32 v155, v83, v151
	v_mul_f32_e32 v156, v84, v151
	v_mul_f32_e32 v157, v85, v151
	v_mul_f32_e32 v154, v130, v154
	v_mul_f32_e32 v155, v131, v155
	v_mul_f32_e32 v156, v132, v156
	v_mul_f32_e32 v157, v133, v157
	v_cvt_pk_bf16_f32 v188, v154, v155
	v_cvt_pk_bf16_f32 v189, v156, v157
	global_store_dwordx2 v183, v[188:189], s[4:5] offset:0
	s_nop 0
	v_mul_f32_e32 v154, v86, v151
	v_mul_f32_e32 v155, v87, v151
	v_mul_f32_e32 v156, v88, v151
	v_mul_f32_e32 v157, v89, v151
	v_mul_f32_e32 v154, v134, v154
	v_mul_f32_e32 v155, v135, v155
	v_mul_f32_e32 v156, v136, v156
	v_mul_f32_e32 v157, v137, v157
	v_cvt_pk_bf16_f32 v188, v154, v155
	v_cvt_pk_bf16_f32 v189, v156, v157
	global_store_dwordx2 v183, v[188:189], s[4:5] offset:512
	s_nop 0
	v_mul_f32_e32 v154, v90, v151
	v_mul_f32_e32 v155, v91, v151
	v_mul_f32_e32 v156, v92, v151
	v_mul_f32_e32 v157, v93, v151
	v_mul_f32_e32 v154, v138, v154
	v_mul_f32_e32 v155, v139, v155
	v_mul_f32_e32 v156, v140, v156
	v_mul_f32_e32 v157, v141, v157
	v_cvt_pk_bf16_f32 v188, v154, v155
	v_cvt_pk_bf16_f32 v189, v156, v157
	global_store_dwordx2 v183, v[188:189], s[4:5] offset:1024
	s_nop 0
	v_mul_f32_e32 v154, v94, v151
	v_mul_f32_e32 v155, v95, v151
	v_mul_f32_e32 v156, v96, v151
	v_mul_f32_e32 v157, v97, v151
	v_mul_f32_e32 v154, v142, v154
	v_mul_f32_e32 v155, v143, v155
	v_mul_f32_e32 v156, v144, v156
	v_mul_f32_e32 v157, v145, v157
	v_cvt_pk_bf16_f32 v188, v154, v155
	v_cvt_pk_bf16_f32 v189, v156, v157
	global_store_dwordx2 v183, v[188:189], s[4:5] offset:1536
	s_nop 0
.Lr0_stx5:
	s_mul_i32 s7, s3, 0x880
	s_add_u32 s4, s4, s7
	s_addc_u32 s5, s5, 0
	s_lshl_b32 s7, s3, 12
	s_add_u32 s0, s0, s7
	s_addc_u32 s1, s1, 0
	s_add_i32 s6, s6, s3
	s_cmpk_ge_u32 s6, 0x4000
	s_cbranch_scc1 .Lr0_stx6
	global_store_dwordx4 v182, v[98:101], s[0:1] offset:0
	global_store_dwordx4 v182, v[102:105], s[0:1] offset:1024
	global_store_dwordx4 v182, v[106:109], s[0:1] offset:2048
	global_store_dwordx4 v182, v[110:113], s[0:1] offset:3072
	v_mul_f32_e32 v154, v98, v152
	v_mul_f32_e32 v155, v99, v152
	v_mul_f32_e32 v156, v100, v152
	v_mul_f32_e32 v157, v101, v152
	v_mul_f32_e32 v154, v130, v154
	v_mul_f32_e32 v155, v131, v155
	v_mul_f32_e32 v156, v132, v156
	v_mul_f32_e32 v157, v133, v157
	v_cvt_pk_bf16_f32 v188, v154, v155
	v_cvt_pk_bf16_f32 v189, v156, v157
	global_store_dwordx2 v183, v[188:189], s[4:5] offset:0
	s_nop 0
	v_mul_f32_e32 v154, v102, v152
	v_mul_f32_e32 v155, v103, v152
	v_mul_f32_e32 v156, v104, v152
	v_mul_f32_e32 v157, v105, v152
	v_mul_f32_e32 v154, v134, v154
	v_mul_f32_e32 v155, v135, v155
	v_mul_f32_e32 v156, v136, v156
	v_mul_f32_e32 v157, v137, v157
	v_cvt_pk_bf16_f32 v188, v154, v155
	v_cvt_pk_bf16_f32 v189, v156, v157
	global_store_dwordx2 v183, v[188:189], s[4:5] offset:512
	s_nop 0
	v_mul_f32_e32 v154, v106, v152
	v_mul_f32_e32 v155, v107, v152
	v_mul_f32_e32 v156, v108, v152
	v_mul_f32_e32 v157, v109, v152
	v_mul_f32_e32 v154, v138, v154
	v_mul_f32_e32 v155, v139, v155
	v_mul_f32_e32 v156, v140, v156
	v_mul_f32_e32 v157, v141, v157
	v_cvt_pk_bf16_f32 v188, v154, v155
	v_cvt_pk_bf16_f32 v189, v156, v157
	global_store_dwordx2 v183, v[188:189], s[4:5] offset:1024
	s_nop 0
	v_mul_f32_e32 v154, v110, v152
	v_mul_f32_e32 v155, v111, v152
	v_mul_f32_e32 v156, v112, v152
	v_mul_f32_e32 v157, v113, v152
	v_mul_f32_e32 v154, v142, v154
	v_mul_f32_e32 v155, v143, v155
	v_mul_f32_e32 v156, v144, v156
	v_mul_f32_e32 v157, v145, v157
	v_cvt_pk_bf16_f32 v188, v154, v155
	v_cvt_pk_bf16_f32 v189, v156, v157
	global_store_dwordx2 v183, v[188:189], s[4:5] offset:1536
	s_nop 0
.Lr0_stx6:
	s_mul_i32 s7, s3, 0x880
	s_add_u32 s4, s4, s7
	s_addc_u32 s5, s5, 0
	s_lshl_b32 s7, s3, 12
	s_add_u32 s0, s0, s7
	s_addc_u32 s1, s1, 0
	s_add_i32 s6, s6, s3
	s_cmpk_ge_u32 s6, 0x4000
	s_cbranch_scc1 .Lr0_stx7
	global_store_dwordx4 v182, v[114:117], s[0:1] offset:0
	global_store_dwordx4 v182, v[118:121], s[0:1] offset:1024
	global_store_dwordx4 v182, v[122:125], s[0:1] offset:2048
	global_store_dwordx4 v182, v[126:129], s[0:1] offset:3072
	v_mul_f32_e32 v154, v114, v153
	v_mul_f32_e32 v155, v115, v153
	v_mul_f32_e32 v156, v116, v153
	v_mul_f32_e32 v157, v117, v153
	v_mul_f32_e32 v154, v130, v154
	v_mul_f32_e32 v155, v131, v155
	v_mul_f32_e32 v156, v132, v156
	v_mul_f32_e32 v157, v133, v157
	v_cvt_pk_bf16_f32 v188, v154, v155
	v_cvt_pk_bf16_f32 v189, v156, v157
	global_store_dwordx2 v183, v[188:189], s[4:5] offset:0
	s_nop 0
	v_mul_f32_e32 v154, v118, v153
	v_mul_f32_e32 v155, v119, v153
	v_mul_f32_e32 v156, v120, v153
	v_mul_f32_e32 v157, v121, v153
	v_mul_f32_e32 v154, v134, v154
	v_mul_f32_e32 v155, v135, v155
	v_mul_f32_e32 v156, v136, v156
	v_mul_f32_e32 v157, v137, v157
	v_cvt_pk_bf16_f32 v188, v154, v155
	v_cvt_pk_bf16_f32 v189, v156, v157
	global_store_dwordx2 v183, v[188:189], s[4:5] offset:512
	s_nop 0
	v_mul_f32_e32 v154, v122, v153
	v_mul_f32_e32 v155, v123, v153
	v_mul_f32_e32 v156, v124, v153
	v_mul_f32_e32 v157, v125, v153
	v_mul_f32_e32 v154, v138, v154
	v_mul_f32_e32 v155, v139, v155
	v_mul_f32_e32 v156, v140, v156
	v_mul_f32_e32 v157, v141, v157
	v_cvt_pk_bf16_f32 v188, v154, v155
	v_cvt_pk_bf16_f32 v189, v156, v157
	global_store_dwordx2 v183, v[188:189], s[4:5] offset:1024
	s_nop 0
	v_mul_f32_e32 v154, v126, v153
	v_mul_f32_e32 v155, v127, v153
	v_mul_f32_e32 v156, v128, v153
	v_mul_f32_e32 v157, v129, v153
	v_mul_f32_e32 v154, v142, v154
	v_mul_f32_e32 v155, v143, v155
	v_mul_f32_e32 v156, v144, v156
	v_mul_f32_e32 v157, v145, v157
	v_cvt_pk_bf16_f32 v188, v154, v155
	v_cvt_pk_bf16_f32 v189, v156, v157
	global_store_dwordx2 v183, v[188:189], s[4:5] offset:1536
	s_nop 0
.Lr0_stx7:
	s_branch .Lr0_next
.Lr0_plain:
	s_mov_b32 s6, s2
	s_mul_i32 s4, s2, 0x880
	s_add_u32 s4, s80, s4
	s_addc_u32 s5, s81, 0
	s_cmpk_ge_u32 s6, 0x4000
	s_cbranch_scc1 .Lr0_stp0
	v_mul_f32_e32 v154, v2, v146
	v_mul_f32_e32 v155, v3, v146
	v_mul_f32_e32 v156, v4, v146
	v_mul_f32_e32 v157, v5, v146
	v_mul_f32_e32 v154, v130, v154
	v_mul_f32_e32 v155, v131, v155
	v_mul_f32_e32 v156, v132, v156
	v_mul_f32_e32 v157, v133, v157
	v_cvt_pk_bf16_f32 v188, v154, v155
	v_cvt_pk_bf16_f32 v189, v156, v157
	global_store_dwordx2 v183, v[188:189], s[4:5] offset:0
	s_nop 0
	v_mul_f32_e32 v154, v6, v146
	v_mul_f32_e32 v155, v7, v146
	v_mul_f32_e32 v156, v8, v146
	v_mul_f32_e32 v157, v9, v146
	v_mul_f32_e32 v154, v134, v154
	v_mul_f32_e32 v155, v135, v155
	v_mul_f32_e32 v156, v136, v156
	v_mul_f32_e32 v157, v137, v157
	v_cvt_pk_bf16_f32 v188, v154, v155
	v_cvt_pk_bf16_f32 v189, v156, v157
	global_store_dwordx2 v183, v[188:189], s[4:5] offset:512
	s_nop 0
	v_mul_f32_e32 v154, v10, v146
	v_mul_f32_e32 v155, v11, v146
	v_mul_f32_e32 v156, v12, v146
	v_mul_f32_e32 v157, v13, v146
	v_mul_f32_e32 v154, v138, v154
	v_mul_f32_e32 v155, v139, v155
	v_mul_f32_e32 v156, v140, v156
	v_mul_f32_e32 v157, v141, v157
	v_cvt_pk_bf16_f32 v188, v154, v155
	v_cvt_pk_bf16_f32 v189, v156, v157
	global_store_dwordx2 v183, v[188:189], s[4:5] offset:1024
	s_nop 0
	v_mul_f32_e32 v154, v14, v146
	v_mul_f32_e32 v155, v15, v146
	v_mul_f32_e32 v156, v16, v146
	v_mul_f32_e32 v157, v17, v146
	v_mul_f32_e32 v154, v142, v154
	v_mul_f32_e32 v155, v143, v155
	v_mul_f32_e32 v156, v144, v156
	v_mul_f32_e32 v157, v145, v157
	v_cvt_pk_bf16_f32 v188, v154, v155
	v_cvt_pk_bf16_f32 v189, v156, v157
	global_store_dwordx2 v183, v[188:189], s[4:5] offset:1536
	s_nop 0
